# scan: waves 4-7 run the chunk MFMA block before the next chunk's decay prep (waves 0-3 keep prep first), so the two halves use LDS/VALU and MFMA at different times
# speedup vs baseline: 1.0089x; 1.0089x over previous
; __device__ __forceinline__ void scan_phase(LAS unsigned char* lds, bf16* proj, int G, int bid) {
;     ...
;         for (int c = 0; c < 272; ++c) {
;             LAS unsigned char* set = lds + (c & 1) * SET;
;             SC_PREP(c + 1);
;             {
;                 const LAS unsigned char* qeb = set + O_QE + fr * QST; const LAS unsigned char* keb = set + O_KE + fr * QST;
;                 bf16x8 kaf[4], qbf[4];
; #pragma unroll
;                 for (int i = 0; i < 4; ++i) { kaf[i] = *(const LAS bf16x8*)(keb + (32 * i + fq * 8) * 2); qbf[i] = *(const LAS bf16x8*)(qeb + (32 * i + fq * 8) * 2); }
;                 u32x2 qlo[4], qhi[4];
; #pragma unroll
;                 for (int i = 0; i < 4; ++i) { qlo[i] = *(const LAS u32x2*)(qeb + (32 * i + fq * 4) * 2); qhi[i] = *(const LAS u32x2*)(qeb + (32 * i + 16 + fq * 4) * 2); }
;                 const bf16x8 vf = *(const LAS bf16x8*)(lds + O_VT + (c % 3) * 8192 + (wave * 16 + fr) * 64 + fq * 16);
;                 f32x4 pt = (f32x4){0.f, 0.f, 0.f, 0.f};
;                 __builtin_amdgcn_s_setprio(1);
; #pragma unroll
;                 for (int i = 0; i < 4; ++i) pt = __builtin_amdgcn_mfma_f32_16x16x32_bf16(kaf[i], qbf[i], pt, 0, 0, 0);
;                 f32x4 oacc = (f32x4){0.f, 0.f, 0.f, 0.f};
; #pragma unroll
;                 for (int i = 0; i < 4; ++i) {
;                     u32x4 sw; sw.x = cvt_pk_bf16(S[2 * i][0], S[2 * i][1]); sw.y = cvt_pk_bf16(S[2 * i][2], S[2 * i][3]); sw.z = cvt_pk_bf16(S[2 * i + 1][0], S[2 * i + 1][1]); sw.w = cvt_pk_bf16(S[2 * i + 1][2], S[2 * i + 1][3]);
;                     u32x4 qw; qw.x = qlo[i][0]; qw.y = qlo[i][1]; qw.z = qhi[i][0]; qw.w = qhi[i][1];
;                     oacc = __builtin_amdgcn_mfma_f32_16x16x32_bf16(__builtin_bit_cast(bf16x8, sw), __builtin_bit_cast(bf16x8, qw), oacc, 0, 0, 0);
;                 }
;                 const LAS float* dv = (const LAS float*)(set + O_DV);
; #pragma unroll
;                 for (int kt = 0; kt < 8; ++kt) {
;                     const f32x4 d4 = *(const LAS f32x4*)(dv + kt * 16 + fq * 4);
;                     const bf16x8 ka = *(const LAS bf16x8*)(set + O_KD + (kt * 16 + fr) * 64 + fq * 16);
;                     S[kt] = __builtin_amdgcn_mfma_f32_16x16x32_bf16(ka, vf, S[kt] * d4, 0, 0, 0);
;                 }
; #pragma unroll
;                 for (int j = 0; j < 4; ++j) pt[j] = (fq * 4 + j <= fr) ? pt[j] : 0.f;
.LBB0_433:
	s_and_b64 vcc, exec, s[38:39]
	s_cbranch_vccz .LscanN_433
	s_add_i32 s7, s6, 1
	s_bitcmp1_b32 s7, 0
	s_cselect_b32 s0, 0x8600, 0
	s_add_i32 s0, s0, 0
	v_lshl_add_u32 v1, v80, 2, s0
	v_lshl_add_u32 v0, v71, 2, v1
	ds_read2_b32 v[48:49], v0 offset1:132
	v_add_u32_e32 v3, 0x2000, v0
	ds_read2_b32 v[50:51], v3 offset0:64 offset1:196
	v_add_u32_e32 v3, 0x400, v0
	ds_read2_b32 v[98:99], v3 offset0:8 offset1:140
	v_add_u32_e32 v0, 0x2400, v0
	ds_read2_b32 v[100:101], v0 offset0:72 offset1:204
	s_waitcnt lgkmcnt(3)
	v_sub_f32_e32 v0, 1.0, v48
	v_max_f32_e32 v3, 0x3bdb8bac, v0
	v_sub_f32_e32 v0, 1.0, v49
	v_max_f32_e32 v0, 0x3bdb8bac, v0
	v_mul_f32_e32 v65, v3, v0
	s_waitcnt lgkmcnt(1)
	v_sub_f32_e32 v0, 1.0, v98
	v_max_f32_e32 v0, 0x3bdb8bac, v0
	v_mul_f32_e32 v104, v65, v0
	v_sub_f32_e32 v0, 1.0, v99
	v_max_f32_e32 v0, 0x3bdb8bac, v0
	v_mul_f32_e32 v105, v104, v0
	v_add3_u32 v1, v1, v90, v72
	s_nop 0
	v_mul_f32_dpp v0, v105, v105 quad_perm:[0,0,1,2] row_mask:0xf bank_mask:0xf bound_ctrl:1
	v_cndmask_b32_e64 v0, v0, v105, s[44:45]
	s_nop 1
	v_mul_f32_dpp v102, v0, v0 quad_perm:[0,0,0,1] row_mask:0xf bank_mask:0xf bound_ctrl:1
	v_cndmask_b32_e64 v102, v0, v102, s[46:47]
	v_mov_b32_e32 v0, 0
	s_nop 1
	v_mov_b32_dpp v0, v102 quad_perm:[0,0,1,2] row_mask:0xf bank_mask:0xf
	v_cndmask_b32_e64 v106, v0, 1.0, s[44:45]
	v_mov_b32_e32 v0, 0
	v_mul_f32_e32 v3, v3, v106
	s_nop 0
	v_mov_b32_dpp v0, v102 quad_perm:[3,3,3,3] row_mask:0xf bank_mask:0xf
	v_rcp_f32_e32 v102, v3
	v_mul_f32_e32 v3, v50, v3
	v_cvt_pk_bf16_f32 v3, v3, s0
	ds_write_b16 v1, v3 offset:16896
	v_mul_f32_e32 v3, v65, v106
	v_rcp_f32_e32 v103, v3
	v_mul_f32_e32 v3, v51, v3
	v_cvt_pk_bf16_f32 v3, v3, s0
	ds_write_b16 v1, v3 offset:17168
	v_mul_f32_e32 v3, v104, v106
	v_rcp_f32_e32 v50, v3
	s_waitcnt lgkmcnt(2)
	v_mul_f32_e32 v3, v100, v3
	v_cvt_pk_bf16_f32 v3, v3, s0
	ds_write_b16 v1, v3 offset:17440
	v_mul_f32_e32 v3, v105, v106
	v_rcp_f32_e32 v51, v3
	v_mul_f32_e32 v3, v101, v3
	v_cvt_pk_bf16_f32 v3, v3, s0
	v_pk_mul_f32 v[48:49], v[48:49], v[102:103]
	ds_write_b16 v1, v3 offset:17712
	v_cvt_pk_bf16_f32 v3, v48, s0
	ds_write_b16 v1, v3 offset:21248
	v_cvt_pk_bf16_f32 v3, v49, s0
	v_pk_mul_f32 v[50:51], v[98:99], v[50:51]
	ds_write_b16 v1, v3 offset:21520
	v_cvt_pk_bf16_f32 v3, v50, s0
	ds_write_b16 v1, v3 offset:21792
	v_cvt_pk_bf16_f32 v3, v51, s0
	v_pk_mul_f32 v[100:101], v[48:49], v[0:1] op_sel_hi:[1,0]
	v_pk_mul_f32 v[98:99], v[50:51], v[0:1] op_sel_hi:[1,0]
	ds_write_b16 v1, v3 offset:22064
	v_add_u32_e32 v1, s0, v83
	v_cvt_pk_bf16_f32 v48, v100, v101
	v_cvt_pk_bf16_f32 v49, v98, v99
	v_add_u32_e32 v3, v1, v55
	ds_write_b64 v3, v[48:49] offset:25600
	s_and_saveexec_b64 s[0:1], s[44:45]
	v_add_u32_e32 v1, v1, v84
	ds_write_b32 v1, v0 offset:33792
	s_or_b64 exec, exec, s[0:1]
	s_mul_hi_u32 s0, s6, 0xaaaaaaab
	s_lshr_b32 s0, s0, 1
	s_bitcmp1_b32 s6, 0
	s_cselect_b32 s1, 0x8600, 0
	s_add_i32 s14, s1, 0
	v_add_u32_e32 v0, s14, v88
	v_add_u32_e32 v1, v0, v89
	ds_read_b128 v[48:51], v1 offset:21248
	ds_read_b128 v[98:101], v1 offset:21312
	ds_read_b128 v[102:105], v1 offset:16896
	ds_read_b128 v[106:109], v1 offset:16960
	ds_read_b128 v[110:113], v1 offset:21376
	ds_read_b128 v[114:117], v1 offset:21440
	ds_read_b128 v[118:121], v1 offset:17024
	ds_read_b128 v[122:125], v1 offset:17088
	v_add_u32_e32 v0, v0, v56
	v_add_u32_e32 v0, 0x4000, v0
	ds_read2_b64 v[126:129], v0 offset0:64 offset1:68
	ds_read2_b64 v[130:133], v0 offset0:72 offset1:76
	ds_read2_b64 v[134:137], v0 offset0:80 offset1:84
	ds_read2_b64 v[138:141], v0 offset0:88 offset1:92
	s_mulk_i32 s0, 0xa000
	v_add_u32_e32 v0, s0, v95
	ds_read_b128 v[142:145], v0
	s_setprio 1
	s_waitcnt lgkmcnt(10)
	v_mfma_f32_16x16x32_bf16 v[48:51], v[48:51], v[102:105], 0
	v_add_u32_e32 v0, s14, v89
	v_add_u32_e32 v1, v0, v57
	v_cvt_pk_bf16_f32 v146, v44, v45
	s_waitcnt lgkmcnt(9)
; #define LAS __attribute__((address_space(3)))
; __device__ __forceinline__ void scan_phase(LAS unsigned char* lds, bf16* proj, int G, int bid) {
;     ...
;                 f32x4 pt = (f32x4){0.f, 0.f, 0.f, 0.f};
;                 __builtin_amdgcn_s_setprio(1);
; #pragma unroll
;                 for (int i = 0; i < 4; ++i) pt = __builtin_amdgcn_mfma_f32_16x16x32_bf16(kaf[i], qbf[i], pt, 0, 0, 0);
;                 f32x4 oacc = (f32x4){0.f, 0.f, 0.f, 0.f};
; #pragma unroll
;                 for (int i = 0; i < 4; ++i) {
;                     u32x4 sw; sw.x = cvt_pk_bf16(S[2 * i][0], S[2 * i][1]); sw.y = cvt_pk_bf16(S[2 * i][2], S[2 * i][3]); sw.z = cvt_pk_bf16(S[2 * i + 1][0], S[2 * i + 1][1]); sw.w = cvt_pk_bf16(S[2 * i + 1][2], S[2 * i + 1][3]);
;                     u32x4 qw; qw.x = qlo[i][0]; qw.y = qlo[i][1]; qw.z = qhi[i][0]; qw.w = qhi[i][1];
;                     oacc = __builtin_amdgcn_mfma_f32_16x16x32_bf16(__builtin_bit_cast(bf16x8, sw), __builtin_bit_cast(bf16x8, qw), oacc, 0, 0, 0);
;                 }
;                 const LAS float* dv = (const LAS float*)(set + O_DV);
; #pragma unroll
;                 for (int kt = 0; kt < 8; ++kt) {
;                     const f32x4 d4 = *(const LAS f32x4*)(dv + kt * 16 + fq * 4);
;                     const bf16x8 ka = *(const LAS bf16x8*)(set + O_KD + (kt * 16 + fr) * 64 + fq * 16);
;                     S[kt] = __builtin_amdgcn_mfma_f32_16x16x32_bf16(ka, vf, S[kt] * d4, 0, 0, 0);
;                 }
; #pragma unroll
;                 for (int j = 0; j < 4; ++j) pt[j] = (fq * 4 + j <= fr) ? pt[j] : 0.f;
;                 u32x4 pw; pw.x = cvt_pk_bf16(pt[0], pt[1]); pw.y = cvt_pk_bf16(pt[2], pt[3]); pw.z = 0u; pw.w = 0u;
;                 oacc = __builtin_amdgcn_mfma_f32_16x16x32_bf16(vf, __builtin_bit_cast(bf16x8, pw), oacc, 0, 0, 0);
;                 __builtin_amdgcn_s_setprio(0);
	v_mfma_f32_16x16x32_bf16 v[48:51], v[98:101], v[106:109], v[48:51]
	ds_read_b128 v[98:101], v1 offset:25600
	ds_read_b128 v[104:107], v0 offset:33792
	v_cvt_pk_bf16_f32 v147, v46, v47
	v_cvt_pk_bf16_f32 v148, v16, v17
	s_waitcnt lgkmcnt(8)
	v_mfma_f32_16x16x32_bf16 v[48:51], v[110:113], v[118:121], v[48:51]
	ds_read_b128 v[108:111], v0 offset:33856
	ds_read_b128 v[118:121], v1 offset:26624
	s_waitcnt lgkmcnt(2)
	v_pk_mul_f32 v[46:47], v[46:47], v[106:107]
	v_pk_mul_f32 v[44:45], v[44:45], v[104:105]
	ds_read_b128 v[158:161], v1 offset:32768
	s_waitcnt lgkmcnt(2)
	v_pk_mul_f32 v[16:17], v[16:17], v[108:109]
	v_mfma_f32_16x16x32_bf16 v[44:47], v[98:101], v[142:145], v[44:47]
	ds_read_b128 v[98:101], v1 offset:27648
	ds_read_b128 v[106:109], v0 offset:33920
	v_cvt_pk_bf16_f32 v149, v18, v19
	v_cvt_pk_bf16_f32 v150, v20, v21
	v_cvt_pk_bf16_f32 v151, v22, v23
	v_pk_mul_f32 v[18:19], v[18:19], v[110:111]
	s_waitcnt lgkmcnt(0)
	v_pk_mul_f32 v[22:23], v[22:23], v[108:109]
	v_pk_mul_f32 v[20:21], v[20:21], v[106:107]
	v_mfma_f32_16x16x32_bf16 v[16:19], v[118:121], v[142:145], v[16:19]
	ds_read_b128 v[110:113], v0 offset:33984
	ds_read_b128 v[118:121], v1 offset:28672
	v_cvt_pk_bf16_f32 v152, v24, v25
	v_cvt_pk_bf16_f32 v153, v26, v27
	v_mfma_f32_16x16x32_bf16 v[20:23], v[98:101], v[142:145], v[20:23]
	ds_read_b128 v[98:101], v1 offset:29696
	ds_read_b128 v[106:109], v0 offset:34048
	s_waitcnt lgkmcnt(3)
	v_pk_mul_f32 v[26:27], v[26:27], v[112:113]
	v_pk_mul_f32 v[24:25], v[24:25], v[110:111]
	v_cvt_pk_bf16_f32 v154, v28, v29
	v_cvt_pk_bf16_f32 v155, v30, v31
	s_waitcnt lgkmcnt(2)
	v_mfma_f32_16x16x32_bf16 v[24:27], v[118:121], v[142:145], v[24:27]
	ds_read_b128 v[110:113], v1 offset:30720
	ds_read_b128 v[118:121], v0 offset:34112
	s_waitcnt lgkmcnt(2)
	v_pk_mul_f32 v[30:31], v[30:31], v[108:109]
	v_pk_mul_f32 v[28:29], v[28:29], v[106:107]
	v_cvt_pk_bf16_f32 v156, v32, v33
	v_cvt_pk_bf16_f32 v157, v34, v35
	v_mfma_f32_16x16x32_bf16 v[28:31], v[98:101], v[142:145], v[28:31]
	ds_read_b128 v[98:101], v0 offset:34176
	s_waitcnt lgkmcnt(1)
	v_pk_mul_f32 v[34:35], v[34:35], v[120:121]
	v_pk_mul_f32 v[32:33], v[32:33], v[118:119]
	v_cvt_pk_bf16_f32 v102, v36, v37
	v_cvt_pk_bf16_f32 v103, v38, v39
	v_mfma_f32_16x16x32_bf16 v[32:35], v[110:113], v[142:145], v[32:35]
	ds_read_b128 v[110:113], v0 offset:34240
	s_waitcnt lgkmcnt(1)
	v_pk_mul_f32 v[38:39], v[38:39], v[100:101]
	v_pk_mul_f32 v[36:37], v[36:37], v[98:99]
	v_mfma_f32_16x16x32_bf16 v[98:101], v[146:149], v[126:129], 0
	v_cvt_pk_bf16_f32 v104, v40, v41
	ds_read_b128 v[106:109], v1 offset:31744
	v_cvt_pk_bf16_f32 v105, v42, v43
	v_mfma_f32_16x16x32_bf16 v[98:101], v[150:153], v[130:133], v[98:101]
	s_waitcnt lgkmcnt(1)
	v_pk_mul_f32 v[42:43], v[42:43], v[112:113]
	v_pk_mul_f32 v[40:41], v[40:41], v[110:111]
	v_mfma_f32_16x16x32_bf16 v[48:51], v[114:117], v[122:125], v[48:51]
	v_mfma_f32_16x16x32_bf16 v[98:101], v[154:157], v[134:137], v[98:101]
	v_mfma_f32_16x16x32_bf16 v[98:101], v[102:105], v[138:141], v[98:101]
	s_nop 5
	v_cvt_pk_bf16_f32 v0, v48, s0
	v_cvt_pk_bf16_f32 v1, v49, s0
	v_cndmask_b32_e64 v0, v0, 0, s[48:49]
	v_cndmask_b32_e64 v1, 0, v1, s[50:51]
	v_perm_b32 v0, v1, v0, s11
	v_cvt_pk_bf16_f32 v1, v50, s0
	v_cvt_pk_bf16_f32 v3, v51, s0
	v_cndmask_b32_e64 v1, v1, 0, s[52:53]
	v_cndmask_b32_e64 v3, v3, 0, s[54:55]
	v_perm_b32 v1, v3, v1, s11
	v_mov_b32_e32 v3, v2
	s_waitcnt lgkmcnt(0)
	v_mfma_f32_16x16x32_bf16 v[36:39], v[106:109], v[142:145], v[36:39]
	v_mfma_f32_16x16x32_bf16 v[40:43], v[158:161], v[142:145], v[40:43]
	v_mfma_f32_16x16x32_bf16 v[48:51], v[142:145], v[0:3], v[98:101]
	s_setprio 0
	s_mov_b64 s[0:1], -1
	s_cmp_gt_u32 s6, 15
	v_add_u32_e32 v1, s4, v53
	s_cbranch_scc0 .LBB0_437
	v_add_u32_e32 v0, 0xffffff00, v1
	v_cndmask_b32_e64 v0, v96, v0, s[56:57]
	v_add_u32_e32 v0, s5, v0
	s_mov_b64 s[0:1], 0

; __device__ __forceinline__ void scan_phase(LAS unsigned char* lds, bf16* proj, int G, int bid) {
;     ...
;             {
;                 const LAS unsigned char* qeb = set + O_QE + fr * QST; const LAS unsigned char* keb = set + O_KE + fr * QST;
;                 bf16x8 kaf[4], qbf[4];
; #pragma unroll
;                 for (int i = 0; i < 4; ++i) { kaf[i] = *(const LAS bf16x8*)(keb + (32 * i + fq * 8) * 2); qbf[i] = *(const LAS bf16x8*)(qeb + (32 * i + fq * 8) * 2); }
;                 u32x2 qlo[4], qhi[4];
; #pragma unroll
;                 for (int i = 0; i < 4; ++i) { qlo[i] = *(const LAS u32x2*)(qeb + (32 * i + fq * 4) * 2); qhi[i] = *(const LAS u32x2*)(qeb + (32 * i + 16 + fq * 4) * 2); }
;                 const bf16x8 vf = *(const LAS bf16x8*)(lds + O_VT + (c % 3) * 8192 + (wave * 16 + fr) * 64 + fq * 16);
;                 f32x4 pt = (f32x4){0.f, 0.f, 0.f, 0.f};
;                 __builtin_amdgcn_s_setprio(1);
; #pragma unroll
;                 for (int i = 0; i < 4; ++i) pt = __builtin_amdgcn_mfma_f32_16x16x32_bf16(kaf[i], qbf[i], pt, 0, 0, 0);
;                 f32x4 oacc = (f32x4){0.f, 0.f, 0.f, 0.f};
; #pragma unroll
;                 for (int i = 0; i < 4; ++i) {
;                     u32x4 sw; sw.x = cvt_pk_bf16(S[2 * i][0], S[2 * i][1]); sw.y = cvt_pk_bf16(S[2 * i][2], S[2 * i][3]); sw.z = cvt_pk_bf16(S[2 * i + 1][0], S[2 * i + 1][1]); sw.w = cvt_pk_bf16(S[2 * i + 1][2], S[2 * i + 1][3]);
;                     u32x4 qw; qw.x = qlo[i][0]; qw.y = qlo[i][1]; qw.z = qhi[i][0]; qw.w = qhi[i][1];
;                     oacc = __builtin_amdgcn_mfma_f32_16x16x32_bf16(__builtin_bit_cast(bf16x8, sw), __builtin_bit_cast(bf16x8, qw), oacc, 0, 0, 0);
;                 }
;                 const LAS float* dv = (const LAS float*)(set + O_DV);
; #pragma unroll
;                 for (int kt = 0; kt < 8; ++kt) {
;                     const f32x4 d4 = *(const LAS f32x4*)(dv + kt * 16 + fq * 4);
;                     const bf16x8 ka = *(const LAS bf16x8*)(set + O_KD + (kt * 16 + fr) * 64 + fq * 16);
;                     S[kt] = __builtin_amdgcn_mfma_f32_16x16x32_bf16(ka, vf, S[kt] * d4, 0, 0, 0);
;                 }
; #pragma unroll
;                 for (int j = 0; j < 4; ++j) pt[j] = (fq * 4 + j <= fr) ? pt[j] : 0.f;
;                 u32x4 pw; pw.x = cvt_pk_bf16(pt[0], pt[1]); pw.y = cvt_pk_bf16(pt[2], pt[3]); pw.z = 0u; pw.w = 0u;
.LscanN_433:
	s_mul_hi_u32 s0, s6, 0xaaaaaaab
	s_lshr_b32 s0, s0, 1
	s_bitcmp1_b32 s6, 0
	s_cselect_b32 s1, 0x8600, 0
	s_add_i32 s14, s1, 0
	v_add_u32_e32 v0, s14, v88
	v_add_u32_e32 v1, v0, v89
	ds_read_b128 v[48:51], v1 offset:21248
	ds_read_b128 v[98:101], v1 offset:21312
	ds_read_b128 v[102:105], v1 offset:16896
	ds_read_b128 v[106:109], v1 offset:16960
	ds_read_b128 v[110:113], v1 offset:21376
	ds_read_b128 v[114:117], v1 offset:21440
	ds_read_b128 v[118:121], v1 offset:17024
	ds_read_b128 v[122:125], v1 offset:17088
	v_add_u32_e32 v0, v0, v56
	v_add_u32_e32 v0, 0x4000, v0
	ds_read2_b64 v[126:129], v0 offset0:64 offset1:68
	ds_read2_b64 v[130:133], v0 offset0:72 offset1:76
	ds_read2_b64 v[134:137], v0 offset0:80 offset1:84
	ds_read2_b64 v[138:141], v0 offset0:88 offset1:92
	s_mulk_i32 s0, 0xa000
	v_add_u32_e32 v0, s0, v95
	ds_read_b128 v[142:145], v0
	s_setprio 1
	s_waitcnt lgkmcnt(10)
	v_mfma_f32_16x16x32_bf16 v[48:51], v[48:51], v[102:105], 0
	v_add_u32_e32 v0, s14, v89
	v_add_u32_e32 v1, v0, v57
	v_cvt_pk_bf16_f32 v146, v44, v45
	s_waitcnt lgkmcnt(9)
	v_mfma_f32_16x16x32_bf16 v[48:51], v[98:101], v[106:109], v[48:51]
	ds_read_b128 v[98:101], v1 offset:25600
	ds_read_b128 v[104:107], v0 offset:33792
	v_cvt_pk_bf16_f32 v147, v46, v47
	v_cvt_pk_bf16_f32 v148, v16, v17
	s_waitcnt lgkmcnt(8)
	v_mfma_f32_16x16x32_bf16 v[48:51], v[110:113], v[118:121], v[48:51]
	ds_read_b128 v[108:111], v0 offset:33856
	ds_read_b128 v[118:121], v1 offset:26624
	s_waitcnt lgkmcnt(2)
	v_pk_mul_f32 v[46:47], v[46:47], v[106:107]
	v_pk_mul_f32 v[44:45], v[44:45], v[104:105]
	ds_read_b128 v[158:161], v1 offset:32768
	s_waitcnt lgkmcnt(2)
	v_pk_mul_f32 v[16:17], v[16:17], v[108:109]
	v_mfma_f32_16x16x32_bf16 v[44:47], v[98:101], v[142:145], v[44:47]
	ds_read_b128 v[98:101], v1 offset:27648
	ds_read_b128 v[106:109], v0 offset:33920
	v_cvt_pk_bf16_f32 v149, v18, v19
	v_cvt_pk_bf16_f32 v150, v20, v21
	v_cvt_pk_bf16_f32 v151, v22, v23
	v_pk_mul_f32 v[18:19], v[18:19], v[110:111]
	s_waitcnt lgkmcnt(0)
	v_pk_mul_f32 v[22:23], v[22:23], v[108:109]
	v_pk_mul_f32 v[20:21], v[20:21], v[106:107]
	v_mfma_f32_16x16x32_bf16 v[16:19], v[118:121], v[142:145], v[16:19]
	ds_read_b128 v[110:113], v0 offset:33984
	ds_read_b128 v[118:121], v1 offset:28672
	v_cvt_pk_bf16_f32 v152, v24, v25
	v_cvt_pk_bf16_f32 v153, v26, v27
	v_mfma_f32_16x16x32_bf16 v[20:23], v[98:101], v[142:145], v[20:23]
	ds_read_b128 v[98:101], v1 offset:29696
	ds_read_b128 v[106:109], v0 offset:34048
	s_waitcnt lgkmcnt(3)
	v_pk_mul_f32 v[26:27], v[26:27], v[112:113]
	v_pk_mul_f32 v[24:25], v[24:25], v[110:111]
	v_cvt_pk_bf16_f32 v154, v28, v29
	v_cvt_pk_bf16_f32 v155, v30, v31
	s_waitcnt lgkmcnt(2)
	v_mfma_f32_16x16x32_bf16 v[24:27], v[118:121], v[142:145], v[24:27]
	ds_read_b128 v[110:113], v1 offset:30720
	ds_read_b128 v[118:121], v0 offset:34112
	s_waitcnt lgkmcnt(2)
	v_pk_mul_f32 v[30:31], v[30:31], v[108:109]
	v_pk_mul_f32 v[28:29], v[28:29], v[106:107]
	v_cvt_pk_bf16_f32 v156, v32, v33
	v_cvt_pk_bf16_f32 v157, v34, v35
	v_mfma_f32_16x16x32_bf16 v[28:31], v[98:101], v[142:145], v[28:31]
	ds_read_b128 v[98:101], v0 offset:34176
	s_waitcnt lgkmcnt(1)
	v_pk_mul_f32 v[34:35], v[34:35], v[120:121]
	v_pk_mul_f32 v[32:33], v[32:33], v[118:119]
	v_cvt_pk_bf16_f32 v102, v36, v37
	v_cvt_pk_bf16_f32 v103, v38, v39
	v_mfma_f32_16x16x32_bf16 v[32:35], v[110:113], v[142:145], v[32:35]
	ds_read_b128 v[110:113], v0 offset:34240
	s_waitcnt lgkmcnt(1)
	v_pk_mul_f32 v[38:39], v[38:39], v[100:101]
	v_pk_mul_f32 v[36:37], v[36:37], v[98:99]
	v_mfma_f32_16x16x32_bf16 v[98:101], v[146:149], v[126:129], 0
	v_cvt_pk_bf16_f32 v104, v40, v41
	ds_read_b128 v[106:109], v1 offset:31744
	v_cvt_pk_bf16_f32 v105, v42, v43
	v_mfma_f32_16x16x32_bf16 v[98:101], v[150:153], v[130:133], v[98:101]
	s_waitcnt lgkmcnt(1)
	v_pk_mul_f32 v[42:43], v[42:43], v[112:113]
	v_pk_mul_f32 v[40:41], v[40:41], v[110:111]
	v_mfma_f32_16x16x32_bf16 v[48:51], v[114:117], v[122:125], v[48:51]
	v_mfma_f32_16x16x32_bf16 v[98:101], v[154:157], v[134:137], v[98:101]
	v_mfma_f32_16x16x32_bf16 v[98:101], v[102:105], v[138:141], v[98:101]
	s_nop 5
	v_cvt_pk_bf16_f32 v0, v48, s0
	v_cvt_pk_bf16_f32 v1, v49, s0
	v_cndmask_b32_e64 v0, v0, 0, s[48:49]
	v_cndmask_b32_e64 v1, 0, v1, s[50:51]
	v_perm_b32 v0, v1, v0, s11
	v_cvt_pk_bf16_f32 v1, v50, s0
	v_cvt_pk_bf16_f32 v3, v51, s0
	v_cndmask_b32_e64 v1, v1, 0, s[52:53]
	v_cndmask_b32_e64 v3, v3, 0, s[54:55]
	v_perm_b32 v1, v3, v1, s11
	v_mov_b32_e32 v3, v2
	s_waitcnt lgkmcnt(0)
	v_mfma_f32_16x16x32_bf16 v[36:39], v[106:109], v[142:145], v[36:39]
	v_mfma_f32_16x16x32_bf16 v[40:43], v[158:161], v[142:145], v[40:43]
	v_mfma_f32_16x16x32_bf16 v[48:51], v[142:145], v[0:3], v[98:101]
	s_setprio 0
	s_mov_b64 s[0:1], -1
	s_cmp_gt_u32 s6, 15
	v_add_u32_e32 v1, s4, v53
	s_cbranch_scc0 .LscanN_437
	v_add_u32_e32 v0, 0xffffff00, v1
	v_cndmask_b32_e64 v0, v96, v0, s[56:57]
	v_add_u32_e32 v0, s5, v0
	s_mov_b64 s[0:1], 0

; __device__ __forceinline__ void scan_phase(LAS unsigned char* lds, bf16* proj, int G, int bid) {
;     ...
;                     *(u32x2*)(proj + (size_t)scan_row16(b, dir, c, fr) * HIN + kcol + wave * 16 + fq * 4) = ow;
.LscanN_439:
	s_nop 0
	v_cvt_pk_bf16_f32 v48, v48, v49
	v_cvt_pk_bf16_f32 v49, v50, v51
	v_mad_i64_i32 v[0:1], s[0:1], v0, s3, v[66:67]
	global_store_dwordx2 v[0:1], v[48:49], off
	s_add_i32 s7, s6, 1
	s_bitcmp1_b32 s7, 0
	s_cselect_b32 s0, 0x8600, 0
	s_add_i32 s0, s0, 0
	v_lshl_add_u32 v1, v80, 2, s0
	v_lshl_add_u32 v0, v71, 2, v1
	ds_read2_b32 v[48:49], v0 offset1:132
	v_add_u32_e32 v3, 0x2000, v0
	ds_read2_b32 v[50:51], v3 offset0:64 offset1:196
	v_add_u32_e32 v3, 0x400, v0
	ds_read2_b32 v[98:99], v3 offset0:8 offset1:140
	v_add_u32_e32 v0, 0x2400, v0
	ds_read2_b32 v[100:101], v0 offset0:72 offset1:204
	s_waitcnt lgkmcnt(3)
	v_sub_f32_e32 v0, 1.0, v48
	v_max_f32_e32 v3, 0x3bdb8bac, v0
	v_sub_f32_e32 v0, 1.0, v49
	v_max_f32_e32 v0, 0x3bdb8bac, v0
	v_mul_f32_e32 v65, v3, v0
	s_waitcnt lgkmcnt(1)
	v_sub_f32_e32 v0, 1.0, v98
	v_max_f32_e32 v0, 0x3bdb8bac, v0
	v_mul_f32_e32 v104, v65, v0
	v_sub_f32_e32 v0, 1.0, v99
	v_max_f32_e32 v0, 0x3bdb8bac, v0
	v_mul_f32_e32 v105, v104, v0
	v_add3_u32 v1, v1, v90, v72
	s_nop 0
	v_mul_f32_dpp v0, v105, v105 quad_perm:[0,0,1,2] row_mask:0xf bank_mask:0xf bound_ctrl:1
	v_cndmask_b32_e64 v0, v0, v105, s[44:45]
	s_nop 1
	v_mul_f32_dpp v102, v0, v0 quad_perm:[0,0,0,1] row_mask:0xf bank_mask:0xf bound_ctrl:1
	v_cndmask_b32_e64 v102, v0, v102, s[46:47]
	v_mov_b32_e32 v0, 0
	s_nop 1
	v_mov_b32_dpp v0, v102 quad_perm:[0,0,1,2] row_mask:0xf bank_mask:0xf
	v_cndmask_b32_e64 v106, v0, 1.0, s[44:45]
	v_mov_b32_e32 v0, 0
	v_mul_f32_e32 v3, v3, v106
	s_nop 0
	v_mov_b32_dpp v0, v102 quad_perm:[3,3,3,3] row_mask:0xf bank_mask:0xf
	v_rcp_f32_e32 v102, v3
	v_mul_f32_e32 v3, v50, v3
	v_cvt_pk_bf16_f32 v3, v3, s0
	ds_write_b16 v1, v3 offset:16896
	v_mul_f32_e32 v3, v65, v106
	v_rcp_f32_e32 v103, v3
	v_mul_f32_e32 v3, v51, v3
	v_cvt_pk_bf16_f32 v3, v3, s0
	ds_write_b16 v1, v3 offset:17168
	v_mul_f32_e32 v3, v104, v106
	v_rcp_f32_e32 v50, v3
	s_waitcnt lgkmcnt(2)
	v_mul_f32_e32 v3, v100, v3
	v_cvt_pk_bf16_f32 v3, v3, s0
	ds_write_b16 v1, v3 offset:17440
	v_mul_f32_e32 v3, v105, v106
	v_rcp_f32_e32 v51, v3
	v_mul_f32_e32 v3, v101, v3
	v_cvt_pk_bf16_f32 v3, v3, s0
	v_pk_mul_f32 v[48:49], v[48:49], v[102:103]
	ds_write_b16 v1, v3 offset:17712
	v_cvt_pk_bf16_f32 v3, v48, s0
	ds_write_b16 v1, v3 offset:21248
	v_cvt_pk_bf16_f32 v3, v49, s0
	v_pk_mul_f32 v[50:51], v[98:99], v[50:51]
	ds_write_b16 v1, v3 offset:21520
	v_cvt_pk_bf16_f32 v3, v50, s0
	ds_write_b16 v1, v3 offset:21792
	v_cvt_pk_bf16_f32 v3, v51, s0
	v_pk_mul_f32 v[100:101], v[48:49], v[0:1] op_sel_hi:[1,0]
	v_pk_mul_f32 v[98:99], v[50:51], v[0:1] op_sel_hi:[1,0]
	ds_write_b16 v1, v3 offset:22064
	v_add_u32_e32 v1, s0, v83
	v_cvt_pk_bf16_f32 v48, v100, v101
	v_cvt_pk_bf16_f32 v49, v98, v99
	v_add_u32_e32 v3, v1, v55
	ds_write_b64 v3, v[48:49] offset:25600
	s_and_saveexec_b64 s[0:1], s[44:45]
	v_add_u32_e32 v1, v1, v84
	ds_write_b32 v1, v0 offset:33792
	s_or_b64 exec, exec, s[0:1]
	s_mov_b64 s[0:1], exec
	s_branch .LBB0_432
